# phase C sel/window: fully valid 64-key blocks (wave-uniform test) skip the per-key mask computation
# speedup vs baseline: 1.0180x; 1.0036x over previous
; template <int MODE>
; DI void nsa_chunk(const KVFrag& f, int kb, int t, bool selbit, const bf16x8 (&qf)[4][2], f32x4 (&O)[4][4], float (&m)[4], float (&l)[4], int quad, bool online) {
;     ...
;   bool val[8];
; #pragma unroll
;   for (int idx = 0; idx < 8; ++idx) {
;     const int key = kb + 8 * quad + idx;
;     val[idx] = MODE == 0 ? (selbit && key <= t) : (key <= t && key > t - 512);
;   }
; template <int MODE>
; DI void nsa_branch(const bf16_t* __restrict__ Kb, const bf16_t* __restrict__ Vtb, unsigned char* lds, int nb, int t, int cur, unsigned selmask, unsigned umall,
;                    const bf16x8 (&qf)[4][2], f32x4 (&O)[4][4], float (&m)[4], float (&l)[4], bool online) {
;     ...
;   for (int n = 0; n < N; n += 2) {
;     const int j = blist[n >> 1];
;     const bool won = MODE == 0 ? ((umall >> j) & 1u) != 0 : (j >= cur - 8 && j <= cur);
;     const bool bit = (selmask >> j) & 1u;
;     ra = *(const u32x4*)(gsrc + (long)kbof(min(n + 2, N - 2)) * gmul);
;     if (won) { KVFrag f; nsa_ldsfrag(f, slot0, qi, quad); nsa_chunk<MODE>(f, j * 64, t, bit, qf, O, m, l, quad, online); }
.LBB0_727:
	s_sub_u32 s58, s56, 0x14c20
	s_lshr_b32 s58, s58, 2
	v_readlane_b32 s0, v216, s58
	s_nop 1
	v_mov_b32_e32 v181, s0
	s_lshl_b32 s10, 1, s0
	s_and_b32 s11, s10, s42
	s_cmp_lg_u32 s11, 0
	s_cselect_b64 s[0:1], -1, 0
	s_add_i32 s57, s54, -1
	s_min_i32 s12, s57, s43
	s_lshr_b32 s12, s12, 1
	v_readlane_b32 s58, v216, s12
	v_and_b32_e32 v116, s10, v171
	v_cmp_ne_u32_e64 s[12:13], 0, v116
	v_cndmask_b32_e64 v116, 0, 1, s[8:9]
	s_lshl_b32 s58, s58, 6
	s_ashr_i32 s59, s58, 31
	s_lshl_b64 s[58:59], s[58:59], 7
	s_cmp_eq_u32 s11, 0
	v_lshl_add_u64 v[112:113], v[168:169], 0, s[58:59]
	global_load_dwordx4 v[112:115], v[112:113], off
	v_cmp_ne_u32_e64 s[10:11], 1, v116
	s_cbranch_scc1 .LBB0_737
	s_and_b64 vcc, exec, s[10:11]
	s_cbranch_vccz .Lmy_nf_s1
	v_readfirstlane_b32 s58, v181
	v_readfirstlane_b32 s59, v160
	s_lshl_b32 s58, s58, 6
	s_add_u32 s60, s58, 63
	s_cmp_le_i32 s60, s59
	s_cbranch_scc0 .Lmy_nf_s1
	ds_read_b128 v[136:139], v176
	ds_read_b128 v[140:143], v176 offset:64
	ds_read_b128 v[144:147], v176 offset:576
	ds_read_b128 v[132:135], v176 offset:640
	ds_read_b128 v[128:131], v177
	ds_read_b128 v[124:127], v177 offset:1280
	ds_read_b128 v[120:123], v177 offset:2560
	ds_read_b128 v[116:119], v177 offset:3840
	v_mov_b32_e32 v226, 0xff800000
	v_cndmask_b32_e64 v218, v226, 0, s[12:13]
	v_cndmask_b32_e64 v219, v226, 0, s[12:13]
	v_cndmask_b32_e64 v220, v226, 0, s[12:13]
	v_cndmask_b32_e64 v221, v226, 0, s[12:13]
	s_branch .Lmy_full_s1
.Lmy_nf_s1:
	v_lshl_or_b32 v182, v181, 6, v173
	v_cmp_le_i32_e32 vcc, v182, v160
	s_and_b64 s[16:17], s[12:13], vcc
	v_cmp_lt_i32_e32 vcc, v182, v160
	v_or_b32_e32 v148, 2, v182
	s_and_b64 s[18:19], s[12:13], vcc
	v_cmp_le_i32_e32 vcc, v148, v160
	v_or_b32_e32 v148, 3, v182
	s_and_b64 s[44:45], s[12:13], vcc
	v_cmp_le_i32_e32 vcc, v148, v160
	v_or_b32_e32 v148, 4, v182
	ds_read_b128 v[136:139], v176
	ds_read_b128 v[140:143], v176 offset:64
	ds_read_b128 v[144:147], v176 offset:576
	ds_read_b128 v[132:135], v176 offset:640
	ds_read_b128 v[128:131], v177
	ds_read_b128 v[124:127], v177 offset:1280
	ds_read_b128 v[120:123], v177 offset:2560
	ds_read_b128 v[116:119], v177 offset:3840
	s_and_b64 s[46:47], s[12:13], vcc
	v_cmp_le_i32_e32 vcc, v148, v160
	v_or_b32_e32 v152, 5, v182
	s_and_b64 s[14:15], s[12:13], vcc
	v_cmp_le_i32_e32 vcc, v152, v160
	v_or_b32_e32 v183, 6, v182
	s_and_b64 s[48:49], s[12:13], vcc
	v_cmp_le_i32_e32 vcc, v183, v160
	v_or_b32_e32 v182, 7, v182
	s_and_b64 s[50:51], s[12:13], vcc
	v_cmp_le_i32_e32 vcc, v182, v160
	s_and_b64 s[52:53], s[12:13], vcc
	s_and_b64 vcc, exec, s[10:11]
	v_mov_b32_e32 v226, 0xff800000
	v_cndmask_b32_e64 v218, v226, 0, s[16:17]
	v_cndmask_b32_e64 v219, v226, 0, s[18:19]
	v_cndmask_b32_e64 v220, v226, 0, s[44:45]
	v_cndmask_b32_e64 v221, v226, 0, s[46:47]
	v_cndmask_b32_e64 v222, v226, 0, s[14:15]
	v_cndmask_b32_e64 v223, v226, 0, s[48:49]
	v_cndmask_b32_e64 v224, v226, 0, s[50:51]
	v_cndmask_b32_e64 v225, v226, 0, s[52:53]
	s_nop 1
	s_cbranch_vccnz .Lmy_fast_s1
	s_waitcnt lgkmcnt(7)
	v_mfma_f32_16x16x32_bf16 v[148:151], v[136:139], v[8:11], v[218:221]
	s_waitcnt lgkmcnt(6)
	v_mfma_f32_16x16x32_bf16 v[152:155], v[140:143], v[12:15], v[148:151]
	s_waitcnt lgkmcnt(5)
	v_mfma_f32_16x16x32_bf16 v[148:151], v[144:147], v[8:11], v[222:225]
	s_waitcnt lgkmcnt(4)
	v_mfma_f32_16x16x32_bf16 v[148:151], v[132:135], v[12:15], v[148:151]
	s_nop 7
	s_cbranch_vccnz .LBB0_730
	v_mul_f32_e32 v182, 0x3e38aa3b, v152
	v_max_f32_e32 v182, 0xf149f2ca, v182
	v_cndmask_b32_e64 v182, v232, v182, s[16:17]
	v_mul_f32_e32 v183, 0x3e38aa3b, v153
	v_max_f32_e32 v183, v182, v183
	v_cndmask_b32_e64 v182, v182, v183, s[18:19]
	v_mul_f32_e32 v183, 0x3e38aa3b, v154
	v_max_f32_e32 v183, v182, v183
	v_cndmask_b32_e64 v182, v182, v183, s[44:45]
	v_mul_f32_e32 v183, 0x3e38aa3b, v155
	v_max_f32_e32 v183, v182, v183
	v_cndmask_b32_e64 v182, v182, v183, s[46:47]
	v_mul_f32_e32 v183, 0x3e38aa3b, v148
	v_max_f32_e32 v183, v182, v183
	v_cndmask_b32_e64 v182, v182, v183, s[14:15]
	v_mul_f32_e32 v183, 0x3e38aa3b, v149
	v_max_f32_e32 v184, v182, v182
	v_max_f32_e32 v183, v184, v183
	v_cndmask_b32_e64 v182, v182, v183, s[48:49]
	v_mul_f32_e32 v183, 0x3e38aa3b, v150
	v_max_f32_e32 v184, v182, v182
	v_max_f32_e32 v183, v184, v183
	v_cndmask_b32_e64 v182, v182, v183, s[50:51]
	v_mul_f32_e32 v183, 0x3e38aa3b, v151
	v_max_f32_e32 v184, v182, v182
	v_max_f32_e32 v183, v184, v183
	v_cndmask_b32_e64 v182, v182, v183, s[52:53]
	ds_bpermute_b32 v183, v175, v182
	v_max_f32_e32 v182, v182, v182
	s_waitcnt lgkmcnt(0)
	v_max_f32_e32 v183, v183, v183
	v_max_f32_e32 v182, v182, v183
	ds_bpermute_b32 v183, v159, v182
	s_waitcnt lgkmcnt(0)
	v_max3_f32 v183, v3, v182, v183
	v_sub_f32_e32 v3, v3, v183
	v_exp_f32_e32 v182, v3
	v_mov_b32_e32 v3, v183
	v_mul_f32_e32 v167, v167, v182
	v_pk_mul_f32 v[106:107], v[106:107], v[182:183] op_sel_hi:[1,0]
	v_pk_mul_f32 v[104:105], v[104:105], v[182:183] op_sel_hi:[1,0]
	v_pk_mul_f32 v[102:103], v[102:103], v[182:183] op_sel_hi:[1,0]
	v_pk_mul_f32 v[100:101], v[100:101], v[182:183] op_sel_hi:[1,0]
	v_pk_mul_f32 v[98:99], v[98:99], v[182:183] op_sel_hi:[1,0]
	v_pk_mul_f32 v[96:97], v[96:97], v[182:183] op_sel_hi:[1,0]
	v_pk_mul_f32 v[94:95], v[94:95], v[182:183] op_sel_hi:[1,0]
	v_pk_mul_f32 v[92:93], v[92:93], v[182:183] op_sel_hi:[1,0]

; template <int MODE>
; DI void nsa_chunk(const KVFrag& f, int kb, int t, bool selbit, const bf16x8 (&qf)[4][2], f32x4 (&O)[4][4], float (&m)[4], float (&l)[4], int quad, bool online) {
;     ...
;   bool val[8];
; #pragma unroll
;   for (int idx = 0; idx < 8; ++idx) {
;     const int key = kb + 8 * quad + idx;
;     val[idx] = MODE == 0 ? (selbit && key <= t) : (key <= t && key > t - 512);
;   }
; template <int MODE>
; DI void nsa_branch(const bf16_t* __restrict__ Kb, const bf16_t* __restrict__ Vtb, unsigned char* lds, int nb, int t, int cur, unsigned selmask, unsigned umall,
;                    const bf16x8 (&qf)[4][2], f32x4 (&O)[4][4], float (&m)[4], float (&l)[4], bool online) {
;     ...
;     *(u32x4*)(slot1 + ldst) = rb;
;     __syncthreads();
;     rb = *(const u32x4*)(gsrc + (long)kbof(min(n + 3, N - 1)) * gmul);
;     if (won) { KVFrag f; nsa_ldsfrag(f, slot1, qi, quad); nsa_chunk<MODE>(f, j * 64 + 32, t, bit, qf, O, m, l, quad, online); }
.LBB0_737:
	s_min_i32 s14, s54, s55
	s_lshr_b32 s14, s14, 1
	v_add_u32_e32 v116, 0x12600, v161
	s_waitcnt vmcnt(1)
	ds_write_b128 v116, v[108:111]
	s_waitcnt lgkmcnt(0)
	s_barrier
	v_readlane_b32 s14, v216, s14
	s_andn2_b64 vcc, exec, s[0:1]
	s_lshl_b32 s14, s14, 6
	s_or_b32 s14, s14, 32
	s_ashr_i32 s15, s14, 31
	s_lshl_b64 s[14:15], s[14:15], 7
	v_lshl_add_u64 v[108:109], v[168:169], 0, s[14:15]
	global_load_dwordx4 v[108:111], v[108:109], off
	s_cbranch_vccnz .LBB0_726
	s_and_b64 vcc, exec, s[10:11]
	s_cbranch_vccz .Lmy_nf_s2
	v_readfirstlane_b32 s58, v181
	v_readfirstlane_b32 s59, v160
	s_lshl_b32 s58, s58, 6
	s_add_u32 s60, s58, 63
	s_cmp_le_i32 s60, s59
	s_cbranch_scc0 .Lmy_nf_s2
	ds_read_b128 v[136:139], v178
	ds_read_b128 v[140:143], v178 offset:64
	ds_read_b128 v[144:147], v178 offset:576
	ds_read_b128 v[132:135], v178 offset:640
	ds_read_b128 v[128:131], v179
	ds_read_b128 v[124:127], v179 offset:1280
	ds_read_b128 v[120:123], v179 offset:2560
	ds_read_b128 v[116:119], v179 offset:3840
	v_mov_b32_e32 v226, 0xff800000
	v_cndmask_b32_e64 v218, v226, 0, s[12:13]
	v_cndmask_b32_e64 v219, v226, 0, s[12:13]
	v_cndmask_b32_e64 v220, v226, 0, s[12:13]
	v_cndmask_b32_e64 v221, v226, 0, s[12:13]
	s_branch .Lmy_full_s2
.Lmy_nf_s2:
	v_lshl_or_b32 v181, v181, 6, v174
	v_cmp_le_i32_e32 vcc, v181, v160
	s_and_b64 s[16:17], s[12:13], vcc
	v_cmp_lt_i32_e32 vcc, v181, v160
	v_or_b32_e32 v148, 2, v181
	s_and_b64 s[18:19], s[12:13], vcc
	v_cmp_le_i32_e32 vcc, v148, v160
	v_or_b32_e32 v148, 3, v181
	s_and_b64 s[44:45], s[12:13], vcc
	v_cmp_le_i32_e32 vcc, v148, v160
	v_or_b32_e32 v148, 4, v181
	ds_read_b128 v[136:139], v178
	ds_read_b128 v[140:143], v178 offset:64
	ds_read_b128 v[144:147], v178 offset:576
	ds_read_b128 v[132:135], v178 offset:640
	ds_read_b128 v[128:131], v179
	ds_read_b128 v[124:127], v179 offset:1280
	ds_read_b128 v[120:123], v179 offset:2560
	ds_read_b128 v[116:119], v179 offset:3840
	s_and_b64 s[46:47], s[12:13], vcc
	v_cmp_le_i32_e32 vcc, v148, v160
	v_or_b32_e32 v152, 5, v181
	s_and_b64 s[14:15], s[12:13], vcc
	v_cmp_le_i32_e32 vcc, v152, v160
	v_or_b32_e32 v182, 6, v181
	s_and_b64 s[48:49], s[12:13], vcc
	v_cmp_le_i32_e32 vcc, v182, v160
	v_or_b32_e32 v181, 7, v181
	s_and_b64 s[50:51], s[12:13], vcc
	v_cmp_le_i32_e32 vcc, v181, v160
	s_and_b64 s[12:13], s[12:13], vcc
	s_and_b64 vcc, exec, s[10:11]
	v_mov_b32_e32 v226, 0xff800000
	v_cndmask_b32_e64 v218, v226, 0, s[16:17]
	v_cndmask_b32_e64 v219, v226, 0, s[18:19]
	v_cndmask_b32_e64 v220, v226, 0, s[44:45]
	v_cndmask_b32_e64 v221, v226, 0, s[46:47]
	v_cndmask_b32_e64 v222, v226, 0, s[14:15]
	v_cndmask_b32_e64 v223, v226, 0, s[48:49]
	v_cndmask_b32_e64 v224, v226, 0, s[50:51]
	v_cndmask_b32_e64 v225, v226, 0, s[12:13]
	s_nop 1
	s_cbranch_vccnz .Lmy_fast_s2
	s_waitcnt lgkmcnt(7)
	v_mfma_f32_16x16x32_bf16 v[148:151], v[136:139], v[8:11], v[218:221]
	s_waitcnt lgkmcnt(6)
	v_mfma_f32_16x16x32_bf16 v[152:155], v[140:143], v[12:15], v[148:151]
	s_waitcnt lgkmcnt(5)
	v_mfma_f32_16x16x32_bf16 v[148:151], v[144:147], v[8:11], v[222:225]
	s_waitcnt lgkmcnt(4)
	v_mfma_f32_16x16x32_bf16 v[148:151], v[132:135], v[12:15], v[148:151]
	s_nop 7
	s_cbranch_vccnz .LBB0_740
	v_mul_f32_e32 v181, 0x3e38aa3b, v152
	v_max_f32_e32 v181, 0xf149f2ca, v181
	v_cndmask_b32_e64 v181, v232, v181, s[16:17]
	v_mul_f32_e32 v182, 0x3e38aa3b, v153
	v_max_f32_e32 v182, v181, v182
	v_cndmask_b32_e64 v181, v181, v182, s[18:19]
	v_mul_f32_e32 v182, 0x3e38aa3b, v154
	v_max_f32_e32 v182, v181, v182
	v_cndmask_b32_e64 v181, v181, v182, s[44:45]
	v_mul_f32_e32 v182, 0x3e38aa3b, v155
	v_max_f32_e32 v182, v181, v182
	v_cndmask_b32_e64 v181, v181, v182, s[46:47]
	v_mul_f32_e32 v182, 0x3e38aa3b, v148
	v_max_f32_e32 v182, v181, v182
	v_cndmask_b32_e64 v181, v181, v182, s[14:15]
	v_mul_f32_e32 v182, 0x3e38aa3b, v149
	v_max_f32_e32 v183, v181, v181
	v_max_f32_e32 v182, v183, v182
	v_cndmask_b32_e64 v181, v181, v182, s[48:49]
	v_mul_f32_e32 v182, 0x3e38aa3b, v150
	v_max_f32_e32 v183, v181, v181
	v_max_f32_e32 v182, v183, v182
	v_cndmask_b32_e64 v181, v181, v182, s[50:51]
	v_mul_f32_e32 v182, 0x3e38aa3b, v151
	v_max_f32_e32 v183, v181, v181
	v_max_f32_e32 v182, v183, v182
	v_cndmask_b32_e64 v181, v181, v182, s[12:13]
	ds_bpermute_b32 v182, v175, v181
	v_max_f32_e32 v181, v181, v181
	s_waitcnt lgkmcnt(0)
	v_max_f32_e32 v182, v182, v182
	v_max_f32_e32 v181, v181, v182
	ds_bpermute_b32 v182, v159, v181
	s_waitcnt lgkmcnt(0)
	v_max3_f32 v181, v3, v181, v182
	v_sub_f32_e32 v3, v3, v181
	v_exp_f32_e32 v182, v3
	v_mov_b32_e32 v3, v181
	v_mul_f32_e32 v167, v167, v182
	v_pk_mul_f32 v[106:107], v[106:107], v[182:183] op_sel_hi:[1,0]
	v_pk_mul_f32 v[104:105], v[104:105], v[182:183] op_sel_hi:[1,0]
	v_pk_mul_f32 v[102:103], v[102:103], v[182:183] op_sel_hi:[1,0]
	v_pk_mul_f32 v[100:101], v[100:101], v[182:183] op_sel_hi:[1,0]
	v_pk_mul_f32 v[98:99], v[98:99], v[182:183] op_sel_hi:[1,0]
	v_pk_mul_f32 v[96:97], v[96:97], v[182:183] op_sel_hi:[1,0]
	v_pk_mul_f32 v[94:95], v[94:95], v[182:183] op_sel_hi:[1,0]
	v_pk_mul_f32 v[92:93], v[92:93], v[182:183] op_sel_hi:[1,0]

; #define MFMA16(a, b, c) __builtin_amdgcn_mfma_f32_16x16x32_bf16((a), (b), (c), 0, 0, 0)
; DI unsigned pk2(float lo, float hi) { f32x2 v = {lo, hi}; bf16x2_t b = __builtin_convertvector(v, bf16x2_t); return __builtin_bit_cast(unsigned, b); }
; template <int MODE>
; DI void nsa_chunk(const KVFrag& f, int kb, int t, bool selbit, const bf16x8 (&qf)[4][2], f32x4 (&O)[4][4], float (&m)[4], float (&l)[4], int quad, bool online) {
;     ...
;   for (int hh = 0; hh < 4; ++hh) {
;     f32x4 s[2];
; #pragma unroll
;     for (int a = 0; a < 2; ++a) { s[a] = MFMA16(f.k[a][0], qf[hh][0], ((f32x4){0.f, 0.f, 0.f, 0.f})); s[a] = MFMA16(f.k[a][1], qf[hh][1], s[a]); }
;     float mn = m[hh];
;     if (online) {
;       float cm = -1e30f;
; #pragma unroll
;       for (int idx = 0; idx < 8; ++idx) if (val[idx]) cm = fmaxf(cm, s[idx >> 2][idx & 3] * SC);
;       cm = fmaxf(cm, __shfl_xor(cm, 16)); cm = fmaxf(cm, __shfl_xor(cm, 32));
;       mn = fmaxf(mn, cm);
;       const float alpha = __builtin_amdgcn_exp2f(m[hh] - mn);
;       m[hh] = mn; l[hh] *= alpha;
; #pragma unroll
;       for (int dt = 0; dt < 4; ++dt) O[hh][dt] = O[hh][dt] * alpha;
;     }
;     float pv[8]; float ps = 0.f;
; #pragma unroll
;     for (int idx = 0; idx < 8; ++idx) { pv[idx] = val[idx] ? __builtin_amdgcn_exp2f(fmaf(s[idx >> 2][idx & 3], SC, -mn)) : 0.f; ps += pv[idx]; }
;     l[hh] += ps;
;     const bf16x8 pf = mk8((u32x4){pk2(pv[0], pv[1]), pk2(pv[2], pv[3]), pk2(pv[4], pv[5]), pk2(pv[6], pv[7])});
; #pragma unroll
;     for (int dt = 0; dt < 4; ++dt) O[hh][dt] = MFMA16(f.v[dt], pf, O[hh][dt]);
;   }
.Lmy_full_s1:
	s_waitcnt lgkmcnt(4)
	v_mfma_f32_16x16x32_bf16 v[182:185], v[136:139], v[8:11], v[218:221]
	v_mfma_f32_16x16x32_bf16 v[182:185], v[140:143], v[12:15], v[182:185]
	v_mfma_f32_16x16x32_bf16 v[186:189], v[144:147], v[8:11], v[218:221]
	v_mfma_f32_16x16x32_bf16 v[186:189], v[132:135], v[12:15], v[186:189]
	v_mfma_f32_16x16x32_bf16 v[190:193], v[136:139], v[16:19], v[218:221]
	v_mfma_f32_16x16x32_bf16 v[190:193], v[140:143], v[20:23], v[190:193]
	v_mfma_f32_16x16x32_bf16 v[194:197], v[144:147], v[16:19], v[218:221]
	v_mfma_f32_16x16x32_bf16 v[194:197], v[132:135], v[20:23], v[194:197]
	s_waitcnt lgkmcnt(0)
	s_nop 2
	v_pk_fma_f32 v[240:241], v[182:183], s[34:35], v[2:3] op_sel:[0,0,1] op_sel_hi:[1,0,1] neg_lo:[0,0,1] neg_hi:[0,0,1]
	v_pk_fma_f32 v[242:243], v[184:185], s[34:35], v[2:3] op_sel:[0,0,1] op_sel_hi:[1,0,1] neg_lo:[0,0,1] neg_hi:[0,0,1]
	v_pk_fma_f32 v[244:245], v[186:187], s[34:35], v[2:3] op_sel:[0,0,1] op_sel_hi:[1,0,1] neg_lo:[0,0,1] neg_hi:[0,0,1]
	v_pk_fma_f32 v[246:247], v[188:189], s[34:35], v[2:3] op_sel:[0,0,1] op_sel_hi:[1,0,1] neg_lo:[0,0,1] neg_hi:[0,0,1]
	v_exp_f32_e32 v240, v240
	v_exp_f32_e32 v241, v241
	v_mfma_f32_16x16x32_bf16 v[182:185], v[136:139], v[24:27], v[218:221]
	v_exp_f32_e32 v242, v242
	v_exp_f32_e32 v243, v243
	v_mfma_f32_16x16x32_bf16 v[182:185], v[140:143], v[28:31], v[182:185]
	v_exp_f32_e32 v244, v244
	v_exp_f32_e32 v245, v245
	v_mfma_f32_16x16x32_bf16 v[186:189], v[144:147], v[24:27], v[218:221]
	v_exp_f32_e32 v246, v246
	v_exp_f32_e32 v247, v247
	v_mfma_f32_16x16x32_bf16 v[186:189], v[132:135], v[28:31], v[186:189]
	v_cvt_pk_bf16_f32 v248, v240, v241
	v_cvt_pk_bf16_f32 v249, v242, v243
	v_cvt_pk_bf16_f32 v250, v244, v245
	v_cvt_pk_bf16_f32 v251, v246, v247
	v_add_f32_e32 v205, 0, v240
	v_add_f32_e32 v205, v241, v205
	v_add_f32_e32 v205, v242, v205
	v_add_f32_e32 v205, v243, v205
	v_add_f32_e32 v205, v244, v205
	v_add_f32_e32 v205, v245, v205
	v_add_f32_e32 v205, v246, v205
	v_add_f32_e32 v205, v247, v205
	v_add_f32_e32 v167, v167, v205
	v_pk_fma_f32 v[240:241], v[190:191], s[34:35], v[2:3] op_sel_hi:[1,0,0] neg_lo:[0,0,1] neg_hi:[0,0,1]
	v_pk_fma_f32 v[242:243], v[192:193], s[34:35], v[2:3] op_sel_hi:[1,0,0] neg_lo:[0,0,1] neg_hi:[0,0,1]
	v_pk_fma_f32 v[244:245], v[194:195], s[34:35], v[2:3] op_sel_hi:[1,0,0] neg_lo:[0,0,1] neg_hi:[0,0,1]
	v_pk_fma_f32 v[246:247], v[196:197], s[34:35], v[2:3] op_sel_hi:[1,0,0] neg_lo:[0,0,1] neg_hi:[0,0,1]
	v_exp_f32_e32 v240, v240
	v_exp_f32_e32 v241, v241
	v_mfma_f32_16x16x32_bf16 v[190:193], v[136:139], v[32:35], v[218:221]
	v_exp_f32_e32 v242, v242
	v_exp_f32_e32 v243, v243
	v_mfma_f32_16x16x32_bf16 v[190:193], v[140:143], v[36:39], v[190:193]
	v_exp_f32_e32 v244, v244
	v_exp_f32_e32 v245, v245
	v_mfma_f32_16x16x32_bf16 v[194:197], v[144:147], v[32:35], v[218:221]
	v_exp_f32_e32 v246, v246
	v_exp_f32_e32 v247, v247
	v_mfma_f32_16x16x32_bf16 v[194:197], v[132:135], v[36:39], v[194:197]
	v_cvt_pk_bf16_f32 v198, v240, v241
	v_cvt_pk_bf16_f32 v199, v242, v243
	v_mfma_f32_16x16x32_bf16 v[104:107], v[128:131], v[248:251], v[104:107]
	v_cvt_pk_bf16_f32 v200, v244, v245
	v_cvt_pk_bf16_f32 v201, v246, v247
	v_mfma_f32_16x16x32_bf16 v[100:103], v[124:127], v[248:251], v[100:103]
	v_add_f32_e32 v205, 0, v240
	v_add_f32_e32 v205, v241, v205
	v_mfma_f32_16x16x32_bf16 v[96:99], v[120:123], v[248:251], v[96:99]
	v_add_f32_e32 v205, v242, v205
	v_add_f32_e32 v205, v243, v205
	v_mfma_f32_16x16x32_bf16 v[92:95], v[116:119], v[248:251], v[92:95]
	v_add_f32_e32 v205, v244, v205
	v_add_f32_e32 v205, v245, v205
	v_add_f32_e32 v205, v246, v205
	v_add_f32_e32 v205, v247, v205
	v_add_f32_e32 v166, v166, v205
	v_pk_fma_f32 v[240:241], v[182:183], s[34:35], v[0:1] op_sel_hi:[1,0,0] neg_lo:[0,0,1] neg_hi:[0,0,1]
	v_pk_fma_f32 v[242:243], v[184:185], s[34:35], v[0:1] op_sel_hi:[1,0,0] neg_lo:[0,0,1] neg_hi:[0,0,1]
	v_pk_fma_f32 v[244:245], v[186:187], s[34:35], v[0:1] op_sel_hi:[1,0,0] neg_lo:[0,0,1] neg_hi:[0,0,1]
	v_pk_fma_f32 v[246:247], v[188:189], s[34:35], v[0:1] op_sel_hi:[1,0,0] neg_lo:[0,0,1] neg_hi:[0,0,1]
	v_exp_f32_e32 v240, v240
	v_exp_f32_e32 v241, v241
	v_mfma_f32_16x16x32_bf16 v[88:91], v[128:131], v[198:201], v[88:91]
	v_exp_f32_e32 v242, v242
	v_exp_f32_e32 v243, v243
	v_mfma_f32_16x16x32_bf16 v[84:87], v[124:127], v[198:201], v[84:87]
	v_exp_f32_e32 v244, v244
	v_exp_f32_e32 v245, v245
	v_mfma_f32_16x16x32_bf16 v[80:83], v[120:123], v[198:201], v[80:83]
	v_exp_f32_e32 v246, v246
	v_exp_f32_e32 v247, v247
	v_mfma_f32_16x16x32_bf16 v[76:79], v[116:119], v[198:201], v[76:79]
	v_cvt_pk_bf16_f32 v248, v240, v241
	v_cvt_pk_bf16_f32 v249, v242, v243
	v_cvt_pk_bf16_f32 v250, v244, v245
	v_cvt_pk_bf16_f32 v251, v246, v247
	v_add_f32_e32 v205, 0, v240
	v_add_f32_e32 v205, v241, v205
	v_add_f32_e32 v205, v242, v205
	v_add_f32_e32 v205, v243, v205
	v_add_f32_e32 v205, v244, v205
	v_add_f32_e32 v205, v245, v205
	v_add_f32_e32 v205, v246, v205
	v_add_f32_e32 v205, v247, v205
	v_add_f32_e32 v165, v165, v205
	v_pk_fma_f32 v[240:241], v[190:191], s[34:35], v[180:181] op_sel_hi:[1,0,0] neg_lo:[0,0,1] neg_hi:[0,0,1]
	v_pk_fma_f32 v[242:243], v[192:193], s[34:35], v[180:181] op_sel_hi:[1,0,0] neg_lo:[0,0,1] neg_hi:[0,0,1]
	v_pk_fma_f32 v[244:245], v[194:195], s[34:35], v[180:181] op_sel_hi:[1,0,0] neg_lo:[0,0,1] neg_hi:[0,0,1]
	v_pk_fma_f32 v[246:247], v[196:197], s[34:35], v[180:181] op_sel_hi:[1,0,0] neg_lo:[0,0,1] neg_hi:[0,0,1]
	v_exp_f32_e32 v240, v240
	v_exp_f32_e32 v241, v241
	v_mfma_f32_16x16x32_bf16 v[72:75], v[128:131], v[248:251], v[72:75]
	v_exp_f32_e32 v242, v242
	v_exp_f32_e32 v243, v243
	v_mfma_f32_16x16x32_bf16 v[68:71], v[124:127], v[248:251], v[68:71]
	v_exp_f32_e32 v244, v244
	v_exp_f32_e32 v245, v245
	v_mfma_f32_16x16x32_bf16 v[64:67], v[120:123], v[248:251], v[64:67]
	v_exp_f32_e32 v246, v246
	v_exp_f32_e32 v247, v247
	v_mfma_f32_16x16x32_bf16 v[60:63], v[116:119], v[248:251], v[60:63]
	v_cvt_pk_bf16_f32 v198, v240, v241
	v_cvt_pk_bf16_f32 v199, v242, v243
	v_cvt_pk_bf16_f32 v200, v244, v245
	v_cvt_pk_bf16_f32 v201, v246, v247
	v_add_f32_e32 v205, 0, v240
	v_add_f32_e32 v205, v241, v205
	v_add_f32_e32 v205, v242, v205
	v_add_f32_e32 v205, v243, v205
	v_add_f32_e32 v205, v244, v205
	v_add_f32_e32 v205, v245, v205
	v_add_f32_e32 v205, v246, v205
	v_add_f32_e32 v205, v247, v205
	v_add_f32_e32 v164, v164, v205
	s_nop 0
	v_mfma_f32_16x16x32_bf16 v[56:59], v[128:131], v[198:201], v[56:59]
	v_mfma_f32_16x16x32_bf16 v[52:55], v[124:127], v[198:201], v[52:55]
	v_mfma_f32_16x16x32_bf16 v[48:51], v[120:123], v[198:201], v[48:51]
	v_mfma_f32_16x16x32_bf16 v[44:47], v[116:119], v[198:201], v[44:47]
	s_branch .LBB0_737

; template <int MODE>
; DI void nsa_chunk(const KVFrag& f, int kb, int t, bool selbit, const bf16x8 (&qf)[4][2], f32x4 (&O)[4][4], float (&m)[4], float (&l)[4], int quad, bool online) {
;     ...
;   bool val[8];
; #pragma unroll
;   for (int idx = 0; idx < 8; ++idx) {
;     const int key = kb + 8 * quad + idx;
;     val[idx] = MODE == 0 ? (selbit && key <= t) : (key <= t && key > t - 512);
;   }
; template <int MODE>
; DI void nsa_branch(const bf16_t* __restrict__ Kb, const bf16_t* __restrict__ Vtb, unsigned char* lds, int nb, int t, int cur, unsigned selmask, unsigned umall,
;                    const bf16x8 (&qf)[4][2], f32x4 (&O)[4][4], float (&m)[4], float (&l)[4], bool online) {
;     ...
;   for (int n = 0; n < N; n += 2) {
;     const int j = blist[n >> 1];
;     const bool won = MODE == 0 ? ((umall >> j) & 1u) != 0 : (j >= cur - 8 && j <= cur);
;     const bool bit = (selmask >> j) & 1u;
;     ra = *(const u32x4*)(gsrc + (long)kbof(min(n + 2, N - 2)) * gmul);
;     if (won) { KVFrag f; nsa_ldsfrag(f, slot0, qi, quad); nsa_chunk<MODE>(f, j * 64, t, bit, qf, O, m, l, quad, online); }
.LBB0_757:
	v_mov_b32_e32 v108, s30
	s_add_i32 s36, s28, -1
	ds_read_b32 v180, v108
	v_min_i32_e32 v108, s36, v168
	v_lshl_add_u32 v108, v108, 1, 32
	v_add_u32_e32 v108, 0x14c00, v108
	ds_read_b32 v108, v108
	s_waitcnt lgkmcnt(1)
	v_cmp_ge_i32_e32 vcc, v180, v156
	v_cmp_le_i32_e64 s[0:1], v180, v170
	v_cndmask_b32_e64 v112, 0, 1, s[44:45]
	s_and_b64 s[54:55], vcc, s[0:1]
	s_waitcnt lgkmcnt(0)
	v_lshlrev_b32_e32 v108, 6, v108
	v_ashrrev_i32_e32 v109, 31, v108
	v_lshlrev_b64 v[108:109], 7, v[108:109]
	v_lshl_add_u64 v[108:109], v[164:165], 0, v[108:109]
	global_load_dwordx4 v[108:111], v[108:109], off
	v_cmp_ne_u32_e64 s[8:9], 1, v112
	s_and_saveexec_b64 s[56:57], s[54:55]
	s_cbranch_execz .LBB0_767
	s_and_b64 vcc, exec, s[8:9]
	s_cbranch_vccz .Lmy_nf_w1
	v_readfirstlane_b32 s58, v180
	v_readfirstlane_b32 s59, v160
	s_lshl_b32 s58, s58, 6
	s_add_u32 s60, s58, 63
	s_cmp_le_i32 s60, s59
	s_cbranch_scc0 .Lmy_nf_w1
	s_sub_u32 s60, s59, 0x1f1
	s_cmp_gt_i32 s58, s60
	s_cbranch_scc0 .Lmy_nf_w1
	ds_read_b128 v[132:135], v174
	ds_read_b128 v[136:139], v174 offset:64
	ds_read_b128 v[140:143], v174 offset:576
	ds_read_b128 v[128:131], v174 offset:640
	ds_read_b128 v[124:127], v176
	ds_read_b128 v[120:123], v176 offset:1280
	ds_read_b128 v[116:119], v176 offset:2560
	ds_read_b128 v[112:115], v176 offset:3840
	s_branch .Lmy_full_w1
.Lmy_nf_w1:
	v_lshl_or_b32 v181, v180, 6, v169
	v_cmp_le_i32_e32 vcc, v181, v160
	v_cmp_gt_i32_e64 s[0:1], v181, v171
	s_and_b64 s[10:11], vcc, s[0:1]
	v_cmp_lt_i32_e32 vcc, v181, v160
	v_cmp_ge_i32_e64 s[0:1], v181, v171
	v_or_b32_e32 v144, 2, v181
	s_and_b64 s[14:15], vcc, s[0:1]
	v_cmp_le_i32_e32 vcc, v144, v160
	v_cmp_gt_i32_e64 s[0:1], v144, v171
	v_or_b32_e32 v144, 3, v181
	s_and_b64 s[18:19], vcc, s[0:1]
	v_cmp_le_i32_e32 vcc, v144, v160
	v_cmp_gt_i32_e64 s[0:1], v144, v171
	v_or_b32_e32 v144, 4, v181
	s_and_b64 s[46:47], vcc, s[0:1]
	v_cmp_le_i32_e32 vcc, v144, v160
	v_cmp_gt_i32_e64 s[0:1], v144, v171
	v_or_b32_e32 v144, 5, v181
	ds_read_b128 v[132:135], v174
	ds_read_b128 v[136:139], v174 offset:64
	ds_read_b128 v[140:143], v174 offset:576
	ds_read_b128 v[128:131], v174 offset:640
	ds_read_b128 v[124:127], v176
	ds_read_b128 v[120:123], v176 offset:1280
	ds_read_b128 v[116:119], v176 offset:2560
	ds_read_b128 v[112:115], v176 offset:3840
	s_and_b64 s[12:13], vcc, s[0:1]
	v_cmp_le_i32_e32 vcc, v144, v160
	v_cmp_gt_i32_e64 s[0:1], v144, v171
	v_or_b32_e32 v148, 6, v181
	s_and_b64 s[16:17], vcc, s[0:1]
	v_cmp_le_i32_e32 vcc, v148, v160
	v_cmp_gt_i32_e64 s[0:1], v148, v171
	v_or_b32_e32 v181, 7, v181
	s_and_b64 s[48:49], vcc, s[0:1]
	v_cmp_le_i32_e32 vcc, v181, v160
	v_cmp_gt_i32_e64 s[0:1], v181, v171
	s_and_b64 s[50:51], vcc, s[0:1]
	s_and_b64 vcc, exec, s[8:9]
	v_mov_b32_e32 v226, 0xff800000
	v_cndmask_b32_e64 v218, v226, 0, s[10:11]
	v_cndmask_b32_e64 v219, v226, 0, s[14:15]
	v_cndmask_b32_e64 v220, v226, 0, s[18:19]
	v_cndmask_b32_e64 v221, v226, 0, s[46:47]
	v_cndmask_b32_e64 v222, v226, 0, s[12:13]
	v_cndmask_b32_e64 v223, v226, 0, s[16:17]
	v_cndmask_b32_e64 v224, v226, 0, s[48:49]
	v_cndmask_b32_e64 v225, v226, 0, s[50:51]
	s_nop 1
	s_cbranch_vccnz .Lmy_fast_w1
	s_waitcnt lgkmcnt(7)
	v_mfma_f32_16x16x32_bf16 v[144:147], v[132:135], v[8:11], v[218:221]
	s_waitcnt lgkmcnt(6)
	v_mfma_f32_16x16x32_bf16 v[148:151], v[136:139], v[12:15], v[144:147]
	s_waitcnt lgkmcnt(5)
	v_mfma_f32_16x16x32_bf16 v[144:147], v[140:143], v[8:11], v[222:225]
	s_waitcnt lgkmcnt(4)
	v_mfma_f32_16x16x32_bf16 v[144:147], v[128:131], v[12:15], v[144:147]
	s_nop 7
	s_cbranch_vccnz .LBB0_760
	v_mul_f32_e32 v181, 0x3e38aa3b, v148
	v_max_f32_e32 v181, 0xf149f2ca, v181
	v_cndmask_b32_e64 v181, v232, v181, s[10:11]
	v_mul_f32_e32 v182, 0x3e38aa3b, v149
	v_max_f32_e32 v182, v181, v182
	v_cndmask_b32_e64 v181, v181, v182, s[14:15]
	v_mul_f32_e32 v182, 0x3e38aa3b, v150
	v_max_f32_e32 v182, v181, v182
	v_cndmask_b32_e64 v181, v181, v182, s[18:19]
	v_mul_f32_e32 v182, 0x3e38aa3b, v151
	v_max_f32_e32 v182, v181, v182
	v_cndmask_b32_e64 v181, v181, v182, s[46:47]
	v_mul_f32_e32 v182, 0x3e38aa3b, v144
	v_max_f32_e32 v182, v181, v182
	v_cndmask_b32_e64 v181, v181, v182, s[12:13]
	v_mul_f32_e32 v182, 0x3e38aa3b, v145
	v_max_f32_e32 v183, v181, v181
	v_max_f32_e32 v182, v183, v182
	v_cndmask_b32_e64 v181, v181, v182, s[16:17]
	v_mul_f32_e32 v182, 0x3e38aa3b, v146
	v_max_f32_e32 v183, v181, v181
	v_max_f32_e32 v182, v183, v182
	v_cndmask_b32_e64 v181, v181, v182, s[48:49]
	v_mul_f32_e32 v182, 0x3e38aa3b, v147
	v_max_f32_e32 v183, v181, v181
	v_max_f32_e32 v182, v183, v182
	v_cndmask_b32_e64 v181, v181, v182, s[50:51]
	ds_bpermute_b32 v182, v175, v181
	v_max_f32_e32 v181, v181, v181
	s_waitcnt lgkmcnt(0)
	v_max_f32_e32 v182, v182, v182
	v_max_f32_e32 v181, v181, v182
	ds_bpermute_b32 v182, v159, v181
	s_waitcnt lgkmcnt(0)
	v_max3_f32 v181, v3, v181, v182
	v_sub_f32_e32 v3, v3, v181
	v_exp_f32_e32 v182, v3
	v_mov_b32_e32 v3, v181
	v_mul_f32_e32 v155, v155, v182
	v_pk_mul_f32 v[102:103], v[102:103], v[182:183] op_sel_hi:[1,0]
	v_pk_mul_f32 v[100:101], v[100:101], v[182:183] op_sel_hi:[1,0]
	v_pk_mul_f32 v[98:99], v[98:99], v[182:183] op_sel_hi:[1,0]
	v_pk_mul_f32 v[96:97], v[96:97], v[182:183] op_sel_hi:[1,0]
	v_pk_mul_f32 v[94:95], v[94:95], v[182:183] op_sel_hi:[1,0]
	v_pk_mul_f32 v[92:93], v[92:93], v[182:183] op_sel_hi:[1,0]
	v_pk_mul_f32 v[90:91], v[90:91], v[182:183] op_sel_hi:[1,0]
	v_pk_mul_f32 v[88:89], v[88:89], v[182:183] op_sel_hi:[1,0]

; template <int MODE>
; DI void nsa_chunk(const KVFrag& f, int kb, int t, bool selbit, const bf16x8 (&qf)[4][2], f32x4 (&O)[4][4], float (&m)[4], float (&l)[4], int quad, bool online) {
;     ...
;   bool val[8];
; #pragma unroll
;   for (int idx = 0; idx < 8; ++idx) {
;     const int key = kb + 8 * quad + idx;
;     val[idx] = MODE == 0 ? (selbit && key <= t) : (key <= t && key > t - 512);
;   }
; template <int MODE>
; DI void nsa_branch(const bf16_t* __restrict__ Kb, const bf16_t* __restrict__ Vtb, unsigned char* lds, int nb, int t, int cur, unsigned selmask, unsigned umall,
;                    const bf16x8 (&qf)[4][2], f32x4 (&O)[4][4], float (&m)[4], float (&l)[4], bool online) {
;     ...
;     *(u32x4*)(slot1 + ldst) = rb;
;     __syncthreads();
;     rb = *(const u32x4*)(gsrc + (long)kbof(min(n + 3, N - 1)) * gmul);
;     if (won) { KVFrag f; nsa_ldsfrag(f, slot1, qi, quad); nsa_chunk<MODE>(f, j * 64 + 32, t, bit, qf, O, m, l, quad, online); }
.LBB0_767:
	s_or_b64 exec, exec, s[56:57]
	v_add_u32_e32 v112, 0x12600, v161
	s_waitcnt vmcnt(1)
	ds_write_b128 v112, v[104:107]
	v_min_i32_e32 v104, s28, v172
	v_lshlrev_b32_e32 v104, 1, v104
	v_and_b32_e32 v104, -4, v104
	v_add_u32_e32 v104, 32, v104
	v_add_u32_e32 v104, 0x14c00, v104
	s_waitcnt lgkmcnt(0)
	s_barrier
	ds_read_b32 v104, v104
	s_waitcnt lgkmcnt(0)
	v_lshl_or_b32 v104, v104, 6, 32
	v_ashrrev_i32_e32 v105, 31, v104
	v_lshlrev_b64 v[104:105], 7, v[104:105]
	v_lshl_add_u64 v[104:105], v[164:165], 0, v[104:105]
	global_load_dwordx4 v[104:107], v[104:105], off
	s_and_saveexec_b64 s[56:57], s[54:55]
	s_cbranch_execz .LBB0_756
	s_and_b64 vcc, exec, s[8:9]
	s_cbranch_vccz .Lmy_nf_w2
	v_readfirstlane_b32 s58, v180
	v_readfirstlane_b32 s59, v160
	s_lshl_b32 s58, s58, 6
	s_add_u32 s60, s58, 63
	s_cmp_le_i32 s60, s59
	s_cbranch_scc0 .Lmy_nf_w2
	s_sub_u32 s60, s59, 0x1f1
	s_cmp_gt_i32 s58, s60
	s_cbranch_scc0 .Lmy_nf_w2
	ds_read_b128 v[132:135], v177
	ds_read_b128 v[136:139], v177 offset:64
	ds_read_b128 v[140:143], v177 offset:576
	ds_read_b128 v[128:131], v177 offset:640
	ds_read_b128 v[124:127], v178
	ds_read_b128 v[120:123], v178 offset:1280
	ds_read_b128 v[116:119], v178 offset:2560
	ds_read_b128 v[112:115], v178 offset:3840
	s_branch .Lmy_full_w2
.Lmy_nf_w2:
	v_lshl_or_b32 v180, v180, 6, v173
	v_cmp_le_i32_e32 vcc, v180, v160
	v_cmp_gt_i32_e64 s[0:1], v180, v171
	s_and_b64 s[10:11], vcc, s[0:1]
	v_cmp_lt_i32_e32 vcc, v180, v160
	v_cmp_ge_i32_e64 s[0:1], v180, v171
	v_or_b32_e32 v144, 2, v180
	s_and_b64 s[14:15], vcc, s[0:1]
	v_cmp_le_i32_e32 vcc, v144, v160
	v_cmp_gt_i32_e64 s[0:1], v144, v171
	v_or_b32_e32 v144, 3, v180
	s_and_b64 s[18:19], vcc, s[0:1]
	v_cmp_le_i32_e32 vcc, v144, v160
	v_cmp_gt_i32_e64 s[0:1], v144, v171
	v_or_b32_e32 v144, 4, v180
	s_and_b64 s[46:47], vcc, s[0:1]
	v_cmp_le_i32_e32 vcc, v144, v160
	v_cmp_gt_i32_e64 s[0:1], v144, v171
	v_or_b32_e32 v144, 5, v180
	ds_read_b128 v[132:135], v177
	ds_read_b128 v[136:139], v177 offset:64
	ds_read_b128 v[140:143], v177 offset:576
	ds_read_b128 v[128:131], v177 offset:640
	ds_read_b128 v[124:127], v178
	ds_read_b128 v[120:123], v178 offset:1280
	ds_read_b128 v[116:119], v178 offset:2560
	ds_read_b128 v[112:115], v178 offset:3840
	s_and_b64 s[12:13], vcc, s[0:1]
	v_cmp_le_i32_e32 vcc, v144, v160
	v_cmp_gt_i32_e64 s[0:1], v144, v171
	v_or_b32_e32 v148, 6, v180
	s_and_b64 s[16:17], vcc, s[0:1]
	v_cmp_le_i32_e32 vcc, v148, v160
	v_cmp_gt_i32_e64 s[0:1], v148, v171
	v_or_b32_e32 v180, 7, v180
	s_and_b64 s[48:49], vcc, s[0:1]
	v_cmp_le_i32_e32 vcc, v180, v160
	v_cmp_gt_i32_e64 s[0:1], v180, v171
	s_and_b64 s[50:51], vcc, s[0:1]
	s_and_b64 vcc, exec, s[8:9]
	v_mov_b32_e32 v226, 0xff800000
	v_cndmask_b32_e64 v218, v226, 0, s[10:11]
	v_cndmask_b32_e64 v219, v226, 0, s[14:15]
	v_cndmask_b32_e64 v220, v226, 0, s[18:19]
	v_cndmask_b32_e64 v221, v226, 0, s[46:47]
	v_cndmask_b32_e64 v222, v226, 0, s[12:13]
	v_cndmask_b32_e64 v223, v226, 0, s[16:17]
	v_cndmask_b32_e64 v224, v226, 0, s[48:49]
	v_cndmask_b32_e64 v225, v226, 0, s[50:51]
	s_nop 1
	s_cbranch_vccnz .Lmy_fast_w2
	s_waitcnt lgkmcnt(7)
	v_mfma_f32_16x16x32_bf16 v[144:147], v[132:135], v[8:11], v[218:221]
	s_waitcnt lgkmcnt(6)
	v_mfma_f32_16x16x32_bf16 v[148:151], v[136:139], v[12:15], v[144:147]
	s_waitcnt lgkmcnt(5)
	v_mfma_f32_16x16x32_bf16 v[144:147], v[140:143], v[8:11], v[222:225]
	s_waitcnt lgkmcnt(4)
	v_mfma_f32_16x16x32_bf16 v[144:147], v[128:131], v[12:15], v[144:147]
	s_nop 7
	s_cbranch_vccnz .LBB0_770
	v_mul_f32_e32 v180, 0x3e38aa3b, v148
	v_max_f32_e32 v180, 0xf149f2ca, v180
	v_cndmask_b32_e64 v180, v232, v180, s[10:11]
	v_mul_f32_e32 v181, 0x3e38aa3b, v149
	v_max_f32_e32 v181, v180, v181
	v_cndmask_b32_e64 v180, v180, v181, s[14:15]
	v_mul_f32_e32 v181, 0x3e38aa3b, v150
	v_max_f32_e32 v181, v180, v181
	v_cndmask_b32_e64 v180, v180, v181, s[18:19]
	v_mul_f32_e32 v181, 0x3e38aa3b, v151
	v_max_f32_e32 v181, v180, v181
	v_cndmask_b32_e64 v180, v180, v181, s[46:47]
	v_mul_f32_e32 v181, 0x3e38aa3b, v144
	v_max_f32_e32 v181, v180, v181
	v_cndmask_b32_e64 v180, v180, v181, s[12:13]
	v_mul_f32_e32 v181, 0x3e38aa3b, v145
	v_max_f32_e32 v182, v180, v180
	v_max_f32_e32 v181, v182, v181
	v_cndmask_b32_e64 v180, v180, v181, s[16:17]
	v_mul_f32_e32 v181, 0x3e38aa3b, v146
	v_max_f32_e32 v182, v180, v180
	v_max_f32_e32 v181, v182, v181
	v_cndmask_b32_e64 v180, v180, v181, s[48:49]
	v_mul_f32_e32 v181, 0x3e38aa3b, v147
	v_max_f32_e32 v182, v180, v180
	v_max_f32_e32 v181, v182, v181
	v_cndmask_b32_e64 v180, v180, v181, s[50:51]
	ds_bpermute_b32 v181, v175, v180
	v_max_f32_e32 v180, v180, v180
	s_waitcnt lgkmcnt(0)
	v_max_f32_e32 v181, v181, v181
	v_max_f32_e32 v180, v180, v181
	ds_bpermute_b32 v181, v159, v180
	s_waitcnt lgkmcnt(0)
	v_max3_f32 v181, v3, v180, v181
	v_sub_f32_e32 v3, v3, v181
	v_exp_f32_e32 v180, v3
	v_mov_b32_e32 v3, v181
	v_mul_f32_e32 v155, v155, v180
	v_pk_mul_f32 v[102:103], v[102:103], v[180:181] op_sel_hi:[1,0]
	v_pk_mul_f32 v[100:101], v[100:101], v[180:181] op_sel_hi:[1,0]
	v_pk_mul_f32 v[98:99], v[98:99], v[180:181] op_sel_hi:[1,0]
	v_pk_mul_f32 v[96:97], v[96:97], v[180:181] op_sel_hi:[1,0]
	v_pk_mul_f32 v[94:95], v[94:95], v[180:181] op_sel_hi:[1,0]
	v_pk_mul_f32 v[92:93], v[92:93], v[180:181] op_sel_hi:[1,0]
	v_pk_mul_f32 v[90:91], v[90:91], v[180:181] op_sel_hi:[1,0]
	v_pk_mul_f32 v[88:89], v[88:89], v[180:181] op_sel_hi:[1,0]

; #define MFMA16(a, b, c) __builtin_amdgcn_mfma_f32_16x16x32_bf16((a), (b), (c), 0, 0, 0)
; DI unsigned pk2(float lo, float hi) { f32x2 v = {lo, hi}; bf16x2_t b = __builtin_convertvector(v, bf16x2_t); return __builtin_bit_cast(unsigned, b); }
; template <int MODE>
; DI void nsa_chunk(const KVFrag& f, int kb, int t, bool selbit, const bf16x8 (&qf)[4][2], f32x4 (&O)[4][4], float (&m)[4], float (&l)[4], int quad, bool online) {
;     ...
;   for (int hh = 0; hh < 4; ++hh) {
;     f32x4 s[2];
; #pragma unroll
;     for (int a = 0; a < 2; ++a) { s[a] = MFMA16(f.k[a][0], qf[hh][0], ((f32x4){0.f, 0.f, 0.f, 0.f})); s[a] = MFMA16(f.k[a][1], qf[hh][1], s[a]); }
;     float mn = m[hh];
;     if (online) {
;       float cm = -1e30f;
; #pragma unroll
;       for (int idx = 0; idx < 8; ++idx) if (val[idx]) cm = fmaxf(cm, s[idx >> 2][idx & 3] * SC);
;       cm = fmaxf(cm, __shfl_xor(cm, 16)); cm = fmaxf(cm, __shfl_xor(cm, 32));
;       mn = fmaxf(mn, cm);
;       const float alpha = __builtin_amdgcn_exp2f(m[hh] - mn);
;       m[hh] = mn; l[hh] *= alpha;
; #pragma unroll
;       for (int dt = 0; dt < 4; ++dt) O[hh][dt] = O[hh][dt] * alpha;
;     }
;     float pv[8]; float ps = 0.f;
; #pragma unroll
;     for (int idx = 0; idx < 8; ++idx) { pv[idx] = val[idx] ? __builtin_amdgcn_exp2f(fmaf(s[idx >> 2][idx & 3], SC, -mn)) : 0.f; ps += pv[idx]; }
;     l[hh] += ps;
;     const bf16x8 pf = mk8((u32x4){pk2(pv[0], pv[1]), pk2(pv[2], pv[3]), pk2(pv[4], pv[5]), pk2(pv[6], pv[7])});
; #pragma unroll
;     for (int dt = 0; dt < 4; ++dt) O[hh][dt] = MFMA16(f.v[dt], pf, O[hh][dt]);
;   }
.Lmy_full_w1:
	s_waitcnt lgkmcnt(4)
	v_mfma_f32_16x16x32_bf16 v[182:185], v[132:135], v[8:11], 0
	v_mfma_f32_16x16x32_bf16 v[182:185], v[136:139], v[12:15], v[182:185]
	v_mfma_f32_16x16x32_bf16 v[186:189], v[140:143], v[8:11], 0
	v_mfma_f32_16x16x32_bf16 v[186:189], v[128:131], v[12:15], v[186:189]
	v_mfma_f32_16x16x32_bf16 v[190:193], v[132:135], v[16:19], 0
	v_mfma_f32_16x16x32_bf16 v[190:193], v[136:139], v[20:23], v[190:193]
	v_mfma_f32_16x16x32_bf16 v[194:197], v[140:143], v[16:19], 0
	v_mfma_f32_16x16x32_bf16 v[194:197], v[128:131], v[20:23], v[194:197]
	s_waitcnt lgkmcnt(0)
	s_nop 2
	v_pk_fma_f32 v[240:241], v[182:183], s[34:35], v[2:3] op_sel:[0,0,1] op_sel_hi:[1,0,1] neg_lo:[0,0,1] neg_hi:[0,0,1]
	v_pk_fma_f32 v[242:243], v[184:185], s[34:35], v[2:3] op_sel:[0,0,1] op_sel_hi:[1,0,1] neg_lo:[0,0,1] neg_hi:[0,0,1]
	v_pk_fma_f32 v[244:245], v[186:187], s[34:35], v[2:3] op_sel:[0,0,1] op_sel_hi:[1,0,1] neg_lo:[0,0,1] neg_hi:[0,0,1]
	v_pk_fma_f32 v[246:247], v[188:189], s[34:35], v[2:3] op_sel:[0,0,1] op_sel_hi:[1,0,1] neg_lo:[0,0,1] neg_hi:[0,0,1]
	v_exp_f32_e32 v240, v240
	v_exp_f32_e32 v241, v241
	v_mfma_f32_16x16x32_bf16 v[182:185], v[132:135], v[24:27], 0
	v_exp_f32_e32 v242, v242
	v_exp_f32_e32 v243, v243
	v_mfma_f32_16x16x32_bf16 v[182:185], v[136:139], v[28:31], v[182:185]
	v_exp_f32_e32 v244, v244
	v_exp_f32_e32 v245, v245
	v_mfma_f32_16x16x32_bf16 v[186:189], v[140:143], v[24:27], 0
	v_exp_f32_e32 v246, v246
	v_exp_f32_e32 v247, v247
	v_mfma_f32_16x16x32_bf16 v[186:189], v[128:131], v[28:31], v[186:189]
	v_cvt_pk_bf16_f32 v248, v240, v241
	v_cvt_pk_bf16_f32 v249, v242, v243
	v_cvt_pk_bf16_f32 v250, v244, v245
	v_cvt_pk_bf16_f32 v251, v246, v247
	v_add_f32_e32 v205, 0, v240
	v_add_f32_e32 v205, v241, v205
	v_add_f32_e32 v205, v242, v205
	v_add_f32_e32 v205, v243, v205
	v_add_f32_e32 v205, v244, v205
	v_add_f32_e32 v205, v245, v205
	v_add_f32_e32 v205, v246, v205
	v_add_f32_e32 v205, v247, v205
	v_add_f32_e32 v155, v155, v205
	v_pk_fma_f32 v[240:241], v[190:191], s[34:35], v[2:3] op_sel_hi:[1,0,0] neg_lo:[0,0,1] neg_hi:[0,0,1]
	v_pk_fma_f32 v[242:243], v[192:193], s[34:35], v[2:3] op_sel_hi:[1,0,0] neg_lo:[0,0,1] neg_hi:[0,0,1]
	v_pk_fma_f32 v[244:245], v[194:195], s[34:35], v[2:3] op_sel_hi:[1,0,0] neg_lo:[0,0,1] neg_hi:[0,0,1]
	v_pk_fma_f32 v[246:247], v[196:197], s[34:35], v[2:3] op_sel_hi:[1,0,0] neg_lo:[0,0,1] neg_hi:[0,0,1]
	v_exp_f32_e32 v240, v240
	v_exp_f32_e32 v241, v241
	v_mfma_f32_16x16x32_bf16 v[190:193], v[132:135], v[32:35], 0
	v_exp_f32_e32 v242, v242
	v_exp_f32_e32 v243, v243
	v_mfma_f32_16x16x32_bf16 v[190:193], v[136:139], v[36:39], v[190:193]
	v_exp_f32_e32 v244, v244
	v_exp_f32_e32 v245, v245
	v_mfma_f32_16x16x32_bf16 v[194:197], v[140:143], v[32:35], 0
	v_exp_f32_e32 v246, v246
	v_exp_f32_e32 v247, v247
	v_mfma_f32_16x16x32_bf16 v[194:197], v[128:131], v[36:39], v[194:197]
	v_cvt_pk_bf16_f32 v198, v240, v241
	v_cvt_pk_bf16_f32 v199, v242, v243
	v_mfma_f32_16x16x32_bf16 v[100:103], v[124:127], v[248:251], v[100:103]
	v_cvt_pk_bf16_f32 v200, v244, v245
	v_cvt_pk_bf16_f32 v201, v246, v247
	v_mfma_f32_16x16x32_bf16 v[96:99], v[120:123], v[248:251], v[96:99]
	v_add_f32_e32 v205, 0, v240
	v_add_f32_e32 v205, v241, v205
	v_mfma_f32_16x16x32_bf16 v[92:95], v[116:119], v[248:251], v[92:95]
	v_add_f32_e32 v205, v242, v205
	v_add_f32_e32 v205, v243, v205
	v_mfma_f32_16x16x32_bf16 v[88:91], v[112:115], v[248:251], v[88:91]
	v_add_f32_e32 v205, v244, v205
	v_add_f32_e32 v205, v245, v205
	v_add_f32_e32 v205, v246, v205
	v_add_f32_e32 v205, v247, v205
	v_add_f32_e32 v154, v154, v205
	v_pk_fma_f32 v[240:241], v[182:183], s[34:35], v[0:1] op_sel_hi:[1,0,0] neg_lo:[0,0,1] neg_hi:[0,0,1]
	v_pk_fma_f32 v[242:243], v[184:185], s[34:35], v[0:1] op_sel_hi:[1,0,0] neg_lo:[0,0,1] neg_hi:[0,0,1]
	v_pk_fma_f32 v[244:245], v[186:187], s[34:35], v[0:1] op_sel_hi:[1,0,0] neg_lo:[0,0,1] neg_hi:[0,0,1]
	v_pk_fma_f32 v[246:247], v[188:189], s[34:35], v[0:1] op_sel_hi:[1,0,0] neg_lo:[0,0,1] neg_hi:[0,0,1]
	v_exp_f32_e32 v240, v240
	v_exp_f32_e32 v241, v241
	v_mfma_f32_16x16x32_bf16 v[84:87], v[124:127], v[198:201], v[84:87]
	v_exp_f32_e32 v242, v242
	v_exp_f32_e32 v243, v243
	v_mfma_f32_16x16x32_bf16 v[80:83], v[120:123], v[198:201], v[80:83]
	v_exp_f32_e32 v244, v244
	v_exp_f32_e32 v245, v245
	v_mfma_f32_16x16x32_bf16 v[76:79], v[116:119], v[198:201], v[76:79]
	v_exp_f32_e32 v246, v246
	v_exp_f32_e32 v247, v247
	v_mfma_f32_16x16x32_bf16 v[72:75], v[112:115], v[198:201], v[72:75]
	v_cvt_pk_bf16_f32 v248, v240, v241
	v_cvt_pk_bf16_f32 v249, v242, v243
	v_cvt_pk_bf16_f32 v250, v244, v245
	v_cvt_pk_bf16_f32 v251, v246, v247
	v_add_f32_e32 v205, 0, v240
	v_add_f32_e32 v205, v241, v205
	v_add_f32_e32 v205, v242, v205
	v_add_f32_e32 v205, v243, v205
	v_add_f32_e32 v205, v244, v205
	v_add_f32_e32 v205, v245, v205
	v_add_f32_e32 v205, v246, v205
	v_add_f32_e32 v205, v247, v205
	v_add_f32_e32 v153, v153, v205
	v_pk_fma_f32 v[240:241], v[190:191], s[34:35], v[178:179] op_sel:[0,0,1] op_sel_hi:[1,0,1] neg_lo:[0,0,1] neg_hi:[0,0,1]
	v_pk_fma_f32 v[242:243], v[192:193], s[34:35], v[178:179] op_sel:[0,0,1] op_sel_hi:[1,0,1] neg_lo:[0,0,1] neg_hi:[0,0,1]
	v_pk_fma_f32 v[244:245], v[194:195], s[34:35], v[178:179] op_sel:[0,0,1] op_sel_hi:[1,0,1] neg_lo:[0,0,1] neg_hi:[0,0,1]
	v_pk_fma_f32 v[246:247], v[196:197], s[34:35], v[178:179] op_sel:[0,0,1] op_sel_hi:[1,0,1] neg_lo:[0,0,1] neg_hi:[0,0,1]
	v_exp_f32_e32 v240, v240
	v_exp_f32_e32 v241, v241
	v_mfma_f32_16x16x32_bf16 v[68:71], v[124:127], v[248:251], v[68:71]
	v_exp_f32_e32 v242, v242
	v_exp_f32_e32 v243, v243
	v_mfma_f32_16x16x32_bf16 v[64:67], v[120:123], v[248:251], v[64:67]
	v_exp_f32_e32 v244, v244
	v_exp_f32_e32 v245, v245
	v_mfma_f32_16x16x32_bf16 v[60:63], v[116:119], v[248:251], v[60:63]
	v_exp_f32_e32 v246, v246
	v_exp_f32_e32 v247, v247
	v_mfma_f32_16x16x32_bf16 v[56:59], v[112:115], v[248:251], v[56:59]
	v_cvt_pk_bf16_f32 v198, v240, v241
	v_cvt_pk_bf16_f32 v199, v242, v243
	v_cvt_pk_bf16_f32 v200, v244, v245
	v_cvt_pk_bf16_f32 v201, v246, v247
	v_add_f32_e32 v205, 0, v240
	v_add_f32_e32 v205, v241, v205
	v_add_f32_e32 v205, v242, v205
	v_add_f32_e32 v205, v243, v205
	v_add_f32_e32 v205, v244, v205
	v_add_f32_e32 v205, v245, v205
	v_add_f32_e32 v205, v246, v205
	v_add_f32_e32 v205, v247, v205
	v_add_f32_e32 v152, v152, v205
	s_nop 0
	v_mfma_f32_16x16x32_bf16 v[52:55], v[124:127], v[198:201], v[52:55]
	v_mfma_f32_16x16x32_bf16 v[48:51], v[120:123], v[198:201], v[48:51]
	v_mfma_f32_16x16x32_bf16 v[44:47], v[116:119], v[198:201], v[44:47]
	v_mfma_f32_16x16x32_bf16 v[40:43], v[112:115], v[198:201], v[40:43]
	s_branch .LBB0_767

; DI int my_tid() { int t = threadIdx.x; asm volatile("" : "+v"(t)); return t; }
; DI Params relaunder(const Params& p0) { Params p = p0; size_t z = 0; asm volatile("" : "+s"(z)); p.ws = p0.ws + z; return p; }
; DI void phaseC(const Params& p0, int layer, unsigned char* lds, bool probe) {
;   const int NITEM = BATCH * 2 * 16;
;   for (int it = blockIdx.x; it < NITEM; it += gridDim.x) {
;     const Params p = relaunder(p0);
;     const int qi5 = it >> 5, qt = qi5 < 8 ? 15 - qi5 : qi5 - 8, bg = it & 31;
;     nsa_wave(p, layer, bg >> 1, bg & 1, qt * 128 + (my_tid() >> 6) * 16, lds, probe ? p.dummy() : p.nz());
;   }
; }
.Lmy_hop_1176:
	s_branch .LBB0_1176
.Lmy_hop_232:
	s_branch .LBB0_232
.LBB0_776:
	v_readlane_b32 s2, v255, 10
	v_readlane_b32 s3, v255, 11
